# ln1_route token loop: the eight modulation-vector row loads issued together with counted vmcnt waits (was four serialised load pairs)
# baseline (speedup 1.0000x reference)
.LBB0_582:
	v_mov_b32_e32 v49, v18
	v_add_u32_e32 v18, 8, v49
	v_readlane_b32 s8, v254, 18
	s_waitcnt vmcnt(0)
	v_lshlrev_b32_e32 v8, 16, v30
	v_and_b32_e32 v9, 0xffff0000, v30
	v_cmp_gt_i32_e32 vcc, s8, v18
	v_add_f32_e32 v12, 0, v8
	v_lshlrev_b32_e32 v10, 16, v31
	v_cndmask_b32_e32 v0, v49, v18, vcc
	v_ashrrev_i32_e32 v1, 31, v0
	v_lshlrev_b64 v[0:1], 11, v[0:1]
	v_lshl_add_u64 v[0:1], v[20:21], 0, v[0:1]
	v_and_b32_e32 v11, 0xffff0000, v31
	v_lshlrev_b32_e32 v42, 16, v28
	v_and_b32_e32 v43, 0xffff0000, v28
	v_lshlrev_b32_e32 v44, 16, v29
	v_and_b32_e32 v45, 0xffff0000, v29
	v_lshlrev_b32_e32 v58, 16, v26
	v_and_b32_e32 v59, 0xffff0000, v26
	v_lshlrev_b32_e32 v61, 16, v27
	v_and_b32_e32 v60, 0xffff0000, v27
	v_lshlrev_b32_e32 v63, 16, v24
	v_and_b32_e32 v62, 0xffff0000, v24
	v_lshlrev_b32_e32 v65, 16, v25
	v_and_b32_e32 v64, 0xffff0000, v25
	global_load_dwordx2 v[30:31], v[0:1], off
	global_load_dwordx2 v[28:29], v[0:1], off offset:512
	global_load_dwordx2 v[26:27], v[0:1], off offset:1024
	global_load_dwordx2 v[24:25], v[0:1], off offset:1536
	s_nop 0
	global_load_dwordx4 v[0:3], v[32:33], off
	global_load_dwordx4 v[4:7], v[34:35], off
	v_add_f32_e32 v12, v12, v9
	v_add_f32_e32 v12, v12, v10
	v_add_f32_e32 v46, v12, v11
	global_load_dwordx4 v[12:15], v[32:33], off offset:1024
	global_load_dwordx4 v[38:41], v[34:35], off offset:1024
	global_load_dwordx4 v[50:53], v[32:33], off offset:2048
	global_load_dwordx4 v[54:57], v[34:35], off offset:2048
	v_add_f32_e32 v46, v46, v42
	v_add_f32_e32 v46, v46, v43
	v_add_f32_e32 v46, v46, v44
	v_add_f32_e32 v46, v46, v45
	v_add_f32_e32 v46, v46, v58
	v_add_f32_e32 v46, v46, v59
	v_add_f32_e32 v46, v46, v61
	v_add_f32_e32 v46, v46, v60
	v_add_f32_e32 v46, v46, v63
	v_add_f32_e32 v46, v46, v62
	v_add_f32_e32 v46, v46, v65
	v_add_f32_e32 v46, v46, v64
	v_cmp_le_i32_e64 s[52:53], s8, v18
	s_mov_b32 s25, 1
	v_add_f32_dpp v46, v46, v46 quad_perm:[1,0,3,2] row_mask:0xf bank_mask:0xf bound_ctrl:1
	s_mov_b32 s26, 0
	s_mov_b32 s27, 0xf149f2ca
	v_add_f32_dpp v46, v46, v46 quad_perm:[2,3,0,1] row_mask:0xf bank_mask:0xf bound_ctrl:1
	s_nop 1
	v_add_f32_dpp v46, v46, v46 row_half_mirror row_mask:0xf bank_mask:0xf bound_ctrl:1
	s_nop 1
	v_add_f32_dpp v46, v46, v46 row_mirror row_mask:0xf bank_mask:0xf bound_ctrl:1
	s_nop 0
	v_readlane_b32 s10, v46, 16
	v_readlane_b32 s11, v46, 48
	v_readlane_b32 s8, v46, 0
	v_readlane_b32 s9, v46, 32
	v_mov_b32_e32 v66, s10
	v_mov_b32_e32 v67, s11
	v_pk_add_f32 v[66:67], s[8:9], v[66:67]
	s_nop 0
	v_add_f32_e32 v46, v66, v67
	v_mul_f32_e32 v46, 0x3a800000, v46
	v_pk_add_f32 v[8:9], v[8:9], v[46:47] op_sel_hi:[1,0] neg_lo:[0,1] neg_hi:[0,1]
	v_pk_add_f32 v[10:11], v[10:11], v[46:47] op_sel_hi:[1,0] neg_lo:[0,1] neg_hi:[0,1]
	v_pk_mul_f32 v[66:67], v[8:9], v[8:9]
	v_pk_mul_f32 v[68:69], v[10:11], v[10:11]
	v_pk_add_f32 v[70:71], v[42:43], v[46:47] op_sel_hi:[1,0] neg_lo:[0,1] neg_hi:[0,1]
	v_pk_add_f32 v[74:75], v[44:45], v[46:47] op_sel_hi:[1,0] neg_lo:[0,1] neg_hi:[0,1]
	v_pk_add_f32 v[58:59], v[58:59], v[46:47] op_sel_hi:[1,0] neg_lo:[0,1] neg_hi:[0,1]
	v_pk_add_f32 v[60:61], v[60:61], v[46:47] op_sel_hi:[1,0] neg_lo:[0,1] neg_hi:[0,1]
	v_pk_add_f32 v[42:43], v[62:63], v[46:47] op_sel_hi:[1,0] neg_lo:[0,1] neg_hi:[0,1]
	v_pk_add_f32 v[44:45], v[64:65], v[46:47] op_sel_hi:[1,0] neg_lo:[0,1] neg_hi:[0,1]
	v_add_f32_e32 v46, v66, v67
	v_add_f32_e32 v46, v68, v46
	v_pk_mul_f32 v[72:73], v[70:71], v[70:71]
	v_add_f32_e32 v46, v69, v46
	v_add_f32_e32 v46, v72, v46
	v_pk_mul_f32 v[76:77], v[74:75], v[74:75]
	v_add_f32_e32 v46, v73, v46
	v_add_f32_e32 v46, v76, v46
	v_pk_mul_f32 v[78:79], v[58:59], v[58:59]
	v_add_f32_e32 v46, v77, v46
	v_add_f32_e32 v46, v78, v46
	v_pk_mul_f32 v[80:81], v[60:61], v[60:61]
	v_add_f32_e32 v46, v79, v46
	v_add_f32_e32 v46, v81, v46
	v_pk_mul_f32 v[62:63], v[42:43], v[42:43]
	v_add_f32_e32 v46, v80, v46
	v_add_f32_e32 v46, v63, v46
	v_pk_mul_f32 v[64:65], v[44:45], v[44:45]
	v_add_f32_e32 v46, v62, v46
	v_add_f32_e32 v46, v65, v46
	v_add_f32_e32 v46, v64, v46
	s_nop 1
	v_add_f32_dpp v46, v46, v46 quad_perm:[1,0,3,2] row_mask:0xf bank_mask:0xf bound_ctrl:1
	s_nop 1
	v_add_f32_dpp v46, v46, v46 quad_perm:[2,3,0,1] row_mask:0xf bank_mask:0xf bound_ctrl:1
	s_nop 1
	v_add_f32_dpp v46, v46, v46 row_half_mirror row_mask:0xf bank_mask:0xf bound_ctrl:1
	s_nop 1
	v_add_f32_dpp v46, v46, v46 row_mirror row_mask:0xf bank_mask:0xf bound_ctrl:1
	s_nop 0
	v_readlane_b32 s10, v46, 16
	v_readlane_b32 s11, v46, 48
	v_readlane_b32 s8, v46, 0
	v_readlane_b32 s9, v46, 32
	v_mov_b32_e32 v62, s10
	v_mov_b32_e32 v63, s11
	v_pk_add_f32 v[62:63], s[8:9], v[62:63]
	s_mov_b32 s8, 0x800000
	v_add_f32_e32 v46, v62, v63
	v_fmamk_f32 v46, v46, 0x3a800000, v194
	v_cmp_gt_f32_e32 vcc, s8, v46
	v_mul_f32_e32 v62, 0x4b800000, v46
	s_mov_b32 s8, 0xfa000000
	v_cndmask_b32_e32 v46, v46, v62, vcc
	v_rsq_f32_e32 v46, v46
	s_nop 0
	v_mul_f32_e32 v62, 0x45800000, v46
	v_cndmask_b32_e32 v46, v46, v62, vcc
	v_pk_mul_f32 v[8:9], v[8:9], v[46:47] op_sel_hi:[1,0]
	v_pk_mul_f32 v[42:43], v[42:43], v[46:47] op_sel_hi:[1,0]
	s_waitcnt vmcnt(4)
	v_pk_fma_f32 v[8:9], v[0:1], v[8:9], v[4:5]
	v_pk_mul_f32 v[0:1], v[10:11], v[46:47] op_sel_hi:[1,0]
	s_nop 0
	v_pk_fma_f32 v[10:11], v[2:3], v[0:1], v[6:7]
	v_pk_mul_f32 v[0:1], v[70:71], v[46:47] op_sel_hi:[1,0]
	s_waitcnt vmcnt(2)
	v_pk_fma_f32 v[38:39], v[12:13], v[0:1], v[38:39]
	v_pk_mul_f32 v[0:1], v[74:75], v[46:47] op_sel_hi:[1,0]
	s_nop 0
	v_pk_fma_f32 v[40:41], v[14:15], v[0:1], v[40:41]
	v_pk_mul_f32 v[0:1], v[58:59], v[46:47] op_sel_hi:[1,0]
	s_waitcnt vmcnt(0)
	v_pk_fma_f32 v[12:13], v[50:51], v[0:1], v[54:55]
	v_pk_mul_f32 v[0:1], v[60:61], v[46:47] op_sel_hi:[1,0]
	s_nop 0
	v_pk_fma_f32 v[14:15], v[52:53], v[0:1], v[56:57] op_sel:[0,1,0] op_sel_hi:[1,0,1]
	global_load_dwordx4 v[0:3], v[32:33], off offset:3072
	global_load_dwordx4 v[4:7], v[34:35], off offset:3072
	s_waitcnt vmcnt(0)
	v_pk_fma_f32 v[50:51], v[0:1], v[42:43], v[4:5] op_sel:[0,1,0] op_sel_hi:[1,0,1]
	v_pk_mul_f32 v[0:1], v[44:45], v[46:47] op_sel_hi:[1,0]
	s_nop 0
	v_pk_fma_f32 v[52:53], v[2:3], v[0:1], v[6:7] op_sel:[0,1,0] op_sel_hi:[1,0,1]
	v_add_co_u32_e32 v2, vcc, s8, v36
	v_cvt_pk_bf16_f32 v0, v8, v9
	v_cvt_pk_bf16_f32 v1, v10, v11
	v_addc_co_u32_e32 v3, vcc, -1, v37, vcc
	global_store_dwordx2 v[2:3], v[0:1], off offset:-1540
	v_cvt_pk_bf16_f32 v0, v38, v39
	v_cvt_pk_bf16_f32 v1, v40, v41
	global_store_dwordx2 v[2:3], v[0:1], off offset:-1028
	v_cvt_pk_bf16_f32 v0, v12, v13
	v_cvt_pk_bf16_f32 v1, v14, v15
	global_store_dwordx2 v[2:3], v[0:1], off offset:-516
	v_cvt_pk_bf16_f32 v0, v50, v51
	v_cvt_pk_bf16_f32 v1, v52, v53
	global_store_dwordx2 v[2:3], v[0:1], off offset:-4
	v_min_i32_e32 v0, 0x2000, v49
	v_ashrrev_i32_e32 v0, 11, v0
	v_mul_hi_i32_i24_e32 v1, 0x6000, v0
	v_mul_i32_i24_e32 v0, 0x6000, v0
	v_lshl_add_u64 v[0:1], s[4:5], 0, v[0:1]
	v_lshl_add_u64 v[0:1], v[0:1], 0, v[192:193]
	s_mov_b64 s[8:9], 0x3000
	v_lshl_add_u64 v[42:43], v[0:1], 0, s[8:9]
	s_movk_i32 s8, 0x4000
	v_add_co_u32_e32 v4, vcc, s8, v0
	v_lshl_add_u64 v[44:45], v[0:1], 0, s[12:13]
	s_nop 0
	v_addc_co_u32_e32 v5, vcc, 0, v1, vcc
	global_load_dwordx4 v[160:163], v[4:5], off offset:-4096
	global_load_dwordx4 v[164:167], v[4:5], off
	global_load_dwordx4 v[168:171], v[42:43], off offset:1024
	global_load_dwordx4 v[172:175], v[44:45], off offset:1024
	global_load_dwordx4 v[176:179], v[42:43], off offset:2048
	global_load_dwordx4 v[180:183], v[44:45], off offset:2048
	global_load_dwordx4 v[184:187], v[42:43], off offset:3072
	global_load_dwordx4 v[156:159], v[44:45], off offset:3072
	s_waitcnt vmcnt(6)
	v_pk_add_f32 v[4:5], v[164:165], 1.0 op_sel_hi:[1,0]
	s_nop 0
	v_pk_fma_f32 v[8:9], v[8:9], v[4:5], v[160:161]
	v_pk_add_f32 v[0:1], v[166:167], 1.0 op_sel_hi:[1,0]
	s_nop 0
	v_pk_fma_f32 v[10:11], v[10:11], v[0:1], v[162:163]
	s_waitcnt vmcnt(4)
	v_pk_add_f32 v[4:5], v[172:173], 1.0 op_sel_hi:[1,0]
	s_nop 0
	v_pk_fma_f32 v[0:1], v[38:39], v[4:5], v[168:169]
	v_pk_add_f32 v[4:5], v[174:175], 1.0 op_sel_hi:[1,0]
	s_nop 0
	v_pk_fma_f32 v[2:3], v[40:41], v[4:5], v[170:171]
	s_waitcnt vmcnt(2)
	v_pk_add_f32 v[38:39], v[180:181], 1.0 op_sel_hi:[1,0]
	s_nop 0
	v_pk_fma_f32 v[4:5], v[12:13], v[38:39], v[176:177]
	v_pk_add_f32 v[12:13], v[182:183], 1.0 op_sel_hi:[1,0]
	s_nop 0
	v_pk_fma_f32 v[6:7], v[14:15], v[12:13], v[178:179]
	s_waitcnt vmcnt(0)
	v_pk_add_f32 v[12:13], v[156:157], 1.0 op_sel_hi:[1,0]
	s_nop 0
	v_pk_fma_f32 v[14:15], v[50:51], v[12:13], v[184:185]
	v_cvt_pk_bf16_f32 v38, v8, v9
	v_cvt_pk_bf16_f32 v39, v10, v11
	v_pk_add_f32 v[12:13], v[158:159], 1.0 op_sel_hi:[1,0]
	global_store_dwordx2 v[36:37], v[38:39], off offset:-1540
	v_cvt_pk_bf16_f32 v38, v0, v1
	v_cvt_pk_bf16_f32 v39, v2, v3
	v_pk_fma_f32 v[12:13], v[52:53], v[12:13], v[186:187]
	global_store_dwordx2 v[36:37], v[38:39], off offset:-1028
	v_cvt_pk_bf16_f32 v38, v4, v5
	v_cvt_pk_bf16_f32 v39, v6, v7
	global_store_dwordx2 v[36:37], v[38:39], off offset:-516
	v_cvt_pk_bf16_f32 v38, v14, v15
	v_cvt_pk_bf16_f32 v39, v12, v13
	global_store_dwordx2 v[36:37], v[38:39], off offset:-4
	ds_read_b128 v[88:91], v22
	ds_read_b128 v[96:99], v22 offset:1024
	ds_read_b128 v[100:103], v22 offset:2048
	ds_read_b128 v[104:107], v22 offset:3072
	ds_read_b128 v[108:111], v22 offset:4096
	ds_read_b128 v[112:115], v22 offset:5120
	ds_read_b128 v[116:119], v22 offset:6144
	ds_read_b128 v[120:123], v22 offset:7168
	ds_read_b128 v[124:127], v22 offset:8192
	ds_read_b128 v[152:155], v22 offset:20480
	s_waitcnt lgkmcnt(9)
	v_mul_f32_e32 v89, v9, v89
	v_fmac_f32_e32 v89, v8, v88
	v_fmac_f32_e32 v89, v10, v90
	v_fmac_f32_e32 v89, v11, v91
	v_add_f32_e32 v42, 0, v89
	ds_read_b128 v[128:131], v22 offset:9216
	s_waitcnt lgkmcnt(9)
	v_mul_f32_e32 v97, v1, v97
	v_fmac_f32_e32 v97, v0, v96
	v_fmac_f32_e32 v97, v2, v98
	v_fmac_f32_e32 v97, v3, v99
	v_add_f32_e32 v42, v42, v97
	ds_read_b128 v[132:135], v22 offset:10240
	s_waitcnt lgkmcnt(9)
	v_mul_f32_e32 v101, v5, v101
	v_fmac_f32_e32 v101, v4, v100
	v_fmac_f32_e32 v101, v6, v102
	v_fmac_f32_e32 v101, v7, v103
	v_add_f32_e32 v42, v42, v101
	ds_read_b128 v[136:139], v22 offset:11264
	s_waitcnt lgkmcnt(9)
	v_mul_f32_e32 v105, v15, v105
	v_fmac_f32_e32 v105, v14, v104
	v_fmac_f32_e32 v105, v12, v106
	v_fmac_f32_e32 v105, v13, v107
	v_add_f32_e32 v38, v42, v105
	ds_read_b128 v[140:143], v22 offset:12288
	s_waitcnt lgkmcnt(9)
	v_mul_f32_e32 v39, v9, v109
	v_fmac_f32_e32 v39, v8, v108
	v_fmac_f32_e32 v39, v10, v110
	v_fmac_f32_e32 v39, v11, v111
	ds_read_b128 v[144:147], v22 offset:13312
	v_add_f32_e32 v39, 0, v39
	s_waitcnt lgkmcnt(9)
	v_mul_f32_e32 v113, v1, v113
	v_fmac_f32_e32 v113, v0, v112
	v_fmac_f32_e32 v113, v2, v114
	v_fmac_f32_e32 v113, v3, v115
	v_add_f32_e32 v39, v39, v113
	ds_read_b128 v[148:151], v22 offset:14336
	s_waitcnt lgkmcnt(9)
	v_mul_f32_e32 v117, v5, v117
	v_fmac_f32_e32 v117, v4, v116
	v_fmac_f32_e32 v117, v6, v118
	v_fmac_f32_e32 v117, v7, v119
	v_add_f32_e32 v39, v39, v117
	ds_read_b128 v[88:91], v22 offset:15360
	s_waitcnt lgkmcnt(9)
	v_mul_f32_e32 v121, v15, v121
	v_fmac_f32_e32 v121, v14, v120
	v_fmac_f32_e32 v121, v12, v122
	v_fmac_f32_e32 v121, v13, v123
	v_add_f32_e32 v39, v39, v121
	ds_read_b128 v[92:95], v22 offset:16384
	s_waitcnt lgkmcnt(9)
	v_mul_f32_e32 v125, v9, v125
	v_fmac_f32_e32 v125, v8, v124
	v_fmac_f32_e32 v125, v10, v126
	v_fmac_f32_e32 v125, v11, v127
	v_add_f32_e32 v44, 0, v125
	ds_read_b128 v[96:99], v22 offset:17408
	s_waitcnt lgkmcnt(8)
	v_mul_f32_e32 v129, v1, v129
	v_fmac_f32_e32 v129, v0, v128
	v_fmac_f32_e32 v129, v2, v130
	v_fmac_f32_e32 v129, v3, v131
	v_add_f32_e32 v44, v44, v129
	ds_read_b128 v[100:103], v22 offset:18432
	s_waitcnt lgkmcnt(8)
	v_mul_f32_e32 v133, v5, v133
	v_fmac_f32_e32 v133, v4, v132
	v_fmac_f32_e32 v133, v6, v134
	v_fmac_f32_e32 v133, v7, v135
	v_add_f32_e32 v44, v44, v133
	s_waitcnt lgkmcnt(7)
	v_mul_f32_e32 v137, v15, v137
	v_fmac_f32_e32 v137, v14, v136
	v_fmac_f32_e32 v137, v12, v138
	v_fmac_f32_e32 v137, v13, v139
	v_add_f32_e32 v40, v44, v137
	ds_read_b128 v[108:111], v22 offset:21504
	s_waitcnt lgkmcnt(7)
	v_mul_f32_e32 v41, v9, v141
	v_fmac_f32_e32 v41, v8, v140
	v_fmac_f32_e32 v41, v10, v142
	v_fmac_f32_e32 v41, v11, v143
	ds_read_b128 v[112:115], v22 offset:22528
	v_add_f32_e32 v41, 0, v41
	s_waitcnt lgkmcnt(7)
	v_mul_f32_e32 v145, v1, v145
	v_fmac_f32_e32 v145, v0, v144
	v_fmac_f32_e32 v145, v2, v146
	v_fmac_f32_e32 v145, v3, v147
	v_add_f32_e32 v41, v41, v145
	ds_read_b128 v[116:119], v22 offset:23552
	s_waitcnt lgkmcnt(7)
	v_mul_f32_e32 v149, v5, v149
	v_fmac_f32_e32 v149, v4, v148
	v_fmac_f32_e32 v149, v6, v150
	v_fmac_f32_e32 v149, v7, v151
	v_add_f32_e32 v41, v41, v149
	ds_read_b128 v[120:123], v22 offset:24576
	s_waitcnt lgkmcnt(7)
	v_mul_f32_e32 v89, v15, v89
	v_fmac_f32_e32 v89, v14, v88
	v_fmac_f32_e32 v89, v12, v90
	v_fmac_f32_e32 v89, v13, v91
	v_add_f32_e32 v41, v41, v89
	ds_read_b128 v[124:127], v22 offset:25600
	s_waitcnt lgkmcnt(7)
	v_mul_f32_e32 v93, v9, v93
	v_fmac_f32_e32 v93, v8, v92
	v_fmac_f32_e32 v93, v10, v94
	v_fmac_f32_e32 v93, v11, v95
	v_add_f32_e32 v46, 0, v93
	ds_read_b128 v[128:131], v22 offset:26624
	s_waitcnt lgkmcnt(7)
	v_mul_f32_e32 v97, v1, v97
	v_fmac_f32_e32 v97, v0, v96
	v_fmac_f32_e32 v97, v2, v98
	v_fmac_f32_e32 v97, v3, v99
	v_add_f32_e32 v46, v46, v97
	ds_read_b128 v[132:135], v22 offset:27648
	s_waitcnt lgkmcnt(7)
	v_mul_f32_e32 v101, v5, v101
	v_fmac_f32_e32 v101, v4, v100
	v_fmac_f32_e32 v101, v6, v102
	v_fmac_f32_e32 v101, v7, v103
	v_add_f32_e32 v46, v46, v101
	ds_read_b128 v[136:139], v22 offset:28672
	ds_read_b128 v[156:159], v22 offset:19456
	s_waitcnt lgkmcnt(0)
	v_mul_f32_e32 v157, v15, v157
	v_fmac_f32_e32 v157, v14, v156
	v_fmac_f32_e32 v157, v12, v158
	v_fmac_f32_e32 v157, v13, v159
	v_add_f32_e32 v42, v46, v157
	v_mul_f32_e32 v43, v9, v153
	v_fmac_f32_e32 v43, v8, v152
	v_fmac_f32_e32 v43, v10, v154
	v_fmac_f32_e32 v43, v11, v155
	ds_read_b128 v[140:143], v22 offset:29696
	v_add_f32_e32 v43, 0, v43
	v_mul_f32_e32 v158, v1, v109
	v_fmac_f32_e32 v158, v0, v108
	v_fmac_f32_e32 v158, v2, v110
	v_fmac_f32_e32 v158, v3, v111
	ds_read_b128 v[144:147], v22 offset:30720
	v_add_f32_e32 v43, v43, v158
	v_mul_f32_e32 v44, v5, v113
	v_fmac_f32_e32 v44, v4, v112
	v_fmac_f32_e32 v44, v6, v114
	v_fmac_f32_e32 v44, v7, v115
	ds_read_b128 v[148:151], v22 offset:31744
	v_add_f32_e32 v43, v43, v44
	v_mul_f32_e32 v44, v15, v117
	v_fmac_f32_e32 v44, v14, v116
	v_fmac_f32_e32 v44, v12, v118
	v_fmac_f32_e32 v44, v13, v119
	ds_read_b128 v[88:91], v22 offset:32768
	v_add_f32_e32 v43, v43, v44
	v_mul_f32_e32 v44, v9, v121
	v_fmac_f32_e32 v44, v8, v120
	v_fmac_f32_e32 v44, v10, v122
	v_fmac_f32_e32 v44, v11, v123
	ds_read_b128 v[92:95], v22 offset:33792
	v_add_f32_e32 v44, 0, v44
	v_mul_f32_e32 v159, v1, v125
	v_fmac_f32_e32 v159, v0, v124
	v_fmac_f32_e32 v159, v2, v126
	v_fmac_f32_e32 v159, v3, v127
	ds_read_b128 v[96:99], v22 offset:34816
	v_add_f32_e32 v44, v44, v159
	v_mul_f32_e32 v45, v5, v129
	v_fmac_f32_e32 v45, v4, v128
	v_fmac_f32_e32 v45, v6, v130
	v_fmac_f32_e32 v45, v7, v131
	ds_read_b128 v[100:103], v22 offset:35840
	v_add_f32_e32 v44, v44, v45
	v_mul_f32_e32 v45, v15, v133
	v_fmac_f32_e32 v45, v14, v132
	v_fmac_f32_e32 v45, v12, v134
	v_fmac_f32_e32 v45, v13, v135
	ds_read_b128 v[104:107], v22 offset:36864
	v_add_f32_e32 v44, v44, v45
	v_mul_f32_e32 v45, v9, v137
	v_fmac_f32_e32 v45, v8, v136
	v_fmac_f32_e32 v45, v10, v138
	v_fmac_f32_e32 v45, v11, v139
	ds_read_b128 v[108:111], v22 offset:37888
	v_add_f32_e32 v45, 0, v45
	s_waitcnt lgkmcnt(8)
	v_mul_f32_e32 v46, v1, v141
	v_fmac_f32_e32 v46, v0, v140
	v_fmac_f32_e32 v46, v2, v142
	v_fmac_f32_e32 v46, v3, v143
	ds_read_b128 v[112:115], v22 offset:38912
	v_add_f32_e32 v45, v45, v46
	s_waitcnt lgkmcnt(8)
	v_mul_f32_e32 v46, v5, v145
	v_fmac_f32_e32 v46, v4, v144
	v_fmac_f32_e32 v46, v6, v146
	v_fmac_f32_e32 v46, v7, v147
	ds_read_b128 v[116:119], v22 offset:39936
	v_add_f32_e32 v45, v45, v46
	s_waitcnt lgkmcnt(8)
	v_mul_f32_e32 v46, v15, v149
	v_fmac_f32_e32 v46, v14, v148
	v_fmac_f32_e32 v46, v12, v150
	v_fmac_f32_e32 v46, v13, v151
	ds_read_b128 v[120:123], v22 offset:40960
	v_add_f32_e32 v45, v45, v46
	s_waitcnt lgkmcnt(8)
	v_mul_f32_e32 v46, v9, v89
	v_fmac_f32_e32 v46, v8, v88
	v_fmac_f32_e32 v46, v10, v90
	v_fmac_f32_e32 v46, v11, v91
	ds_read_b128 v[124:127], v22 offset:41984
	v_add_f32_e32 v46, 0, v46
	s_waitcnt lgkmcnt(8)
	v_mul_f32_e32 v49, v1, v93
	v_fmac_f32_e32 v49, v0, v92
	v_fmac_f32_e32 v49, v2, v94
	v_fmac_f32_e32 v49, v3, v95
	ds_read_b128 v[128:131], v22 offset:43008
	v_add_f32_e32 v46, v46, v49
	s_waitcnt lgkmcnt(8)
	v_mul_f32_e32 v49, v5, v97
	v_fmac_f32_e32 v49, v4, v96
	v_fmac_f32_e32 v49, v6, v98
	v_fmac_f32_e32 v49, v7, v99
	ds_read_b128 v[132:135], v22 offset:44032
	v_add_f32_e32 v46, v46, v49
	s_waitcnt lgkmcnt(8)
	v_mul_f32_e32 v49, v15, v101
	v_fmac_f32_e32 v49, v14, v100
	v_fmac_f32_e32 v49, v12, v102
	v_fmac_f32_e32 v49, v13, v103
	ds_read_b128 v[136:139], v22 offset:45056
	v_add_f32_e32 v46, v46, v49
	s_waitcnt lgkmcnt(8)
	v_mul_f32_e32 v49, v9, v105
	v_fmac_f32_e32 v49, v8, v104
	v_fmac_f32_e32 v49, v10, v106
	v_fmac_f32_e32 v49, v11, v107
	ds_read_b128 v[140:143], v22 offset:46080
	v_add_f32_e32 v49, 0, v49
	s_waitcnt lgkmcnt(8)
	v_mul_f32_e32 v109, v1, v109
	v_fmac_f32_e32 v109, v0, v108
	v_fmac_f32_e32 v109, v2, v110
	v_fmac_f32_e32 v109, v3, v111
	v_add_f32_e32 v49, v49, v109
	ds_read_b128 v[144:147], v22 offset:47104
	s_waitcnt lgkmcnt(8)
	v_mul_f32_e32 v113, v5, v113
	v_fmac_f32_e32 v113, v4, v112
	v_fmac_f32_e32 v113, v6, v114
	v_fmac_f32_e32 v113, v7, v115
	v_add_f32_e32 v49, v49, v113
	ds_read_b128 v[148:151], v22 offset:48128
	s_waitcnt lgkmcnt(8)
	v_mul_f32_e32 v117, v15, v117
	v_fmac_f32_e32 v117, v14, v116
	v_fmac_f32_e32 v117, v12, v118
	v_fmac_f32_e32 v117, v13, v119
	v_add_f32_e32 v49, v49, v117
	ds_read_b128 v[88:91], v22 offset:49152
	s_waitcnt lgkmcnt(8)
	v_mul_f32_e32 v121, v9, v121
	v_fmac_f32_e32 v121, v8, v120
	v_fmac_f32_e32 v121, v10, v122
	v_fmac_f32_e32 v121, v11, v123
	v_add_f32_e32 v54, 0, v121
	ds_read_b128 v[92:95], v22 offset:50176
	s_waitcnt lgkmcnt(8)
	v_mul_f32_e32 v125, v1, v125
	v_fmac_f32_e32 v125, v0, v124
	v_fmac_f32_e32 v125, v2, v126
	v_fmac_f32_e32 v125, v3, v127
	v_add_f32_e32 v54, v54, v125
	ds_read_b128 v[96:99], v22 offset:51200
	s_waitcnt lgkmcnt(8)
	v_mul_f32_e32 v129, v5, v129
	v_fmac_f32_e32 v129, v4, v128
	v_fmac_f32_e32 v129, v6, v130
	v_fmac_f32_e32 v129, v7, v131
	v_add_f32_e32 v54, v54, v129
	ds_read_b128 v[100:103], v22 offset:52224
	s_waitcnt lgkmcnt(8)
	v_mul_f32_e32 v133, v15, v133
	v_fmac_f32_e32 v133, v14, v132
	v_fmac_f32_e32 v133, v12, v134
	v_fmac_f32_e32 v133, v13, v135
	v_add_f32_e32 v50, v54, v133
	ds_read_b128 v[104:107], v22 offset:53248
	s_waitcnt lgkmcnt(8)
	v_mul_f32_e32 v51, v9, v137
	v_fmac_f32_e32 v51, v8, v136
	v_fmac_f32_e32 v51, v10, v138
	v_fmac_f32_e32 v51, v11, v139
	ds_read_b128 v[108:111], v22 offset:54272
	v_add_f32_e32 v51, 0, v51
	s_waitcnt lgkmcnt(8)
	v_mul_f32_e32 v141, v1, v141
	v_fmac_f32_e32 v141, v0, v140
	v_fmac_f32_e32 v141, v2, v142
	v_fmac_f32_e32 v141, v3, v143
	v_add_f32_e32 v51, v51, v141
	ds_read_b128 v[112:115], v22 offset:55296
	s_waitcnt lgkmcnt(8)
	v_mul_f32_e32 v145, v5, v145
	v_fmac_f32_e32 v145, v4, v144
	v_fmac_f32_e32 v145, v6, v146
	v_fmac_f32_e32 v145, v7, v147
	v_add_f32_e32 v51, v51, v145
	ds_read_b128 v[116:119], v22 offset:56320
	s_waitcnt lgkmcnt(8)
	v_mul_f32_e32 v149, v15, v149
	v_fmac_f32_e32 v149, v14, v148
	v_fmac_f32_e32 v149, v12, v150
	v_fmac_f32_e32 v149, v13, v151
	v_add_f32_e32 v51, v51, v149
	ds_read_b128 v[120:123], v22 offset:57344
	s_waitcnt lgkmcnt(8)
	v_mul_f32_e32 v89, v9, v89
	v_fmac_f32_e32 v89, v8, v88
	v_fmac_f32_e32 v89, v10, v90
	v_fmac_f32_e32 v89, v11, v91
	v_add_f32_e32 v56, 0, v89
	ds_read_b128 v[124:127], v22 offset:58368
	s_waitcnt lgkmcnt(8)
	v_mul_f32_e32 v93, v1, v93
	v_fmac_f32_e32 v93, v0, v92
	v_fmac_f32_e32 v93, v2, v94
	v_fmac_f32_e32 v93, v3, v95
	v_add_f32_e32 v56, v56, v93
	ds_read_b128 v[128:131], v22 offset:59392
	s_waitcnt lgkmcnt(8)
	v_mul_f32_e32 v97, v5, v97
	v_fmac_f32_e32 v97, v4, v96
	v_fmac_f32_e32 v97, v6, v98
	v_fmac_f32_e32 v97, v7, v99
	v_add_f32_e32 v56, v56, v97
	ds_read_b128 v[132:135], v22 offset:60416
	s_waitcnt lgkmcnt(8)
	v_mul_f32_e32 v101, v15, v101
	v_fmac_f32_e32 v101, v14, v100
	v_fmac_f32_e32 v101, v12, v102
	v_fmac_f32_e32 v101, v13, v103
	v_add_f32_e32 v52, v56, v101
	ds_read_b128 v[136:139], v22 offset:61440
	s_waitcnt lgkmcnt(8)
	v_mul_f32_e32 v53, v9, v105
	v_fmac_f32_e32 v53, v8, v104
	v_fmac_f32_e32 v53, v10, v106
	v_fmac_f32_e32 v53, v11, v107
	ds_read_b128 v[140:143], v22 offset:62464
	v_add_f32_e32 v53, 0, v53
	s_waitcnt lgkmcnt(8)
	v_mul_f32_e32 v109, v1, v109
	v_fmac_f32_e32 v109, v0, v108
	v_fmac_f32_e32 v109, v2, v110
	v_fmac_f32_e32 v109, v3, v111
	v_add_f32_e32 v53, v53, v109
	ds_read_b128 v[144:147], v22 offset:63488
	s_waitcnt lgkmcnt(8)
	v_mul_f32_e32 v113, v5, v113
	v_fmac_f32_e32 v113, v4, v112
	v_fmac_f32_e32 v113, v6, v114
	v_fmac_f32_e32 v113, v7, v115
	v_add_f32_e32 v53, v53, v113
	ds_read_b128 v[148:151], v22 offset:64512
	s_waitcnt lgkmcnt(8)
	v_mul_f32_e32 v117, v15, v117
	v_fmac_f32_e32 v117, v14, v116
	v_fmac_f32_e32 v117, v12, v118
	v_fmac_f32_e32 v117, v13, v119
	v_add_f32_e32 v53, v53, v117
	s_waitcnt lgkmcnt(7)
	v_mul_f32_e32 v121, v9, v121
	v_fmac_f32_e32 v121, v8, v120
	v_fmac_f32_e32 v121, v10, v122
	v_fmac_f32_e32 v121, v11, v123
	v_add_f32_e32 v58, 0, v121
	s_waitcnt lgkmcnt(6)
	v_mul_f32_e32 v125, v1, v125
	v_fmac_f32_e32 v125, v0, v124
	v_fmac_f32_e32 v125, v2, v126
	v_fmac_f32_e32 v125, v3, v127
	v_add_f32_e32 v58, v58, v125
	s_waitcnt lgkmcnt(5)
	v_mul_f32_e32 v129, v5, v129
	v_fmac_f32_e32 v129, v4, v128
	v_fmac_f32_e32 v129, v6, v130
	v_fmac_f32_e32 v129, v7, v131
	v_add_f32_e32 v58, v58, v129
	s_waitcnt lgkmcnt(4)
	v_mul_f32_e32 v133, v15, v133
	v_fmac_f32_e32 v133, v14, v132
	v_fmac_f32_e32 v133, v12, v134
	v_fmac_f32_e32 v133, v13, v135
	v_add_f32_e32 v58, v58, v133
	s_waitcnt lgkmcnt(3)
	v_mul_f32_e32 v9, v9, v137
	v_fmac_f32_e32 v9, v8, v136
	v_fmac_f32_e32 v9, v10, v138
	v_fmac_f32_e32 v9, v11, v139
	v_add_f32_e32 v54, 0, v9
	s_waitcnt lgkmcnt(2)
	v_mul_f32_e32 v1, v1, v141
	v_fmac_f32_e32 v1, v0, v140
	v_fmac_f32_e32 v1, v2, v142
	v_fmac_f32_e32 v1, v3, v143
	v_add_f32_e32 v8, v54, v1
	s_waitcnt lgkmcnt(1)
	v_mul_f32_e32 v145, v5, v145
	v_fmac_f32_e32 v145, v4, v144
	v_fmac_f32_e32 v145, v6, v146
	v_fmac_f32_e32 v145, v7, v147
	v_add_f32_e32 v4, v8, v145
	v_cndmask_b32_e64 v5, v51, v41, s[42:43]
	v_cndmask_b32_e64 v6, v52, v42, s[42:43]
	v_cndmask_b32_e64 v7, v53, v43, s[42:43]
	v_cndmask_b32_e64 v8, v58, v44, s[42:43]
	s_waitcnt lgkmcnt(0)
	v_mul_f32_e32 v149, v15, v149
	v_fmac_f32_e32 v149, v14, v148
	v_fmac_f32_e32 v149, v12, v150
	v_fmac_f32_e32 v149, v13, v151
	v_add_f32_e32 v0, v4, v149
	v_cndmask_b32_e64 v1, v38, v46, s[42:43]
	v_cndmask_b32_e64 v2, v46, v38, s[42:43]
	v_cndmask_b32_e64 v3, v49, v39, s[42:43]
	v_cndmask_b32_e64 v4, v50, v40, s[42:43]
	v_add_f32_dpp v1, v1, v2 quad_perm:[1,0,3,2] row_mask:0xf bank_mask:0xf bound_ctrl:1
	v_cndmask_b32_e64 v2, v39, v49, s[42:43]
	s_nop 1
	v_add_f32_dpp v2, v2, v3 quad_perm:[1,0,3,2] row_mask:0xf bank_mask:0xf bound_ctrl:1
	v_cndmask_b32_e64 v3, v40, v50, s[42:43]
	s_nop 1
	v_add_f32_dpp v3, v3, v4 quad_perm:[1,0,3,2] row_mask:0xf bank_mask:0xf bound_ctrl:1
	v_cndmask_b32_e64 v4, v41, v51, s[42:43]
	s_nop 1
	v_add_f32_dpp v4, v4, v5 quad_perm:[1,0,3,2] row_mask:0xf bank_mask:0xf bound_ctrl:1
	v_cndmask_b32_e64 v5, v42, v52, s[42:43]
	s_nop 1
	v_add_f32_dpp v5, v5, v6 quad_perm:[1,0,3,2] row_mask:0xf bank_mask:0xf bound_ctrl:1
	v_cndmask_b32_e64 v6, v43, v53, s[42:43]
	s_nop 1
	v_add_f32_dpp v6, v6, v7 quad_perm:[1,0,3,2] row_mask:0xf bank_mask:0xf bound_ctrl:1
	v_cndmask_b32_e64 v7, v44, v58, s[42:43]
	s_nop 1
	v_add_f32_dpp v7, v7, v8 quad_perm:[1,0,3,2] row_mask:0xf bank_mask:0xf bound_ctrl:1
	v_cndmask_b32_e64 v8, v45, v0, s[42:43]
	v_cndmask_b32_e64 v0, v0, v45, s[42:43]
	s_nop 1
	v_add_f32_dpp v0, v8, v0 quad_perm:[1,0,3,2] row_mask:0xf bank_mask:0xf bound_ctrl:1
	v_cndmask_b32_e64 v8, v1, v5, s[44:45]
	v_cndmask_b32_e64 v1, v5, v1, s[44:45]
	v_cndmask_b32_e64 v5, v2, v6, s[44:45]
	v_cndmask_b32_e64 v2, v6, v2, s[44:45]
	v_add_f32_dpp v1, v8, v1 quad_perm:[2,3,0,1] row_mask:0xf bank_mask:0xf bound_ctrl:1
	s_nop 0
	v_add_f32_dpp v2, v5, v2 quad_perm:[2,3,0,1] row_mask:0xf bank_mask:0xf bound_ctrl:1
	v_cndmask_b32_e64 v5, v3, v7, s[44:45]
	v_cndmask_b32_e64 v3, v7, v3, s[44:45]
	s_nop 1
	v_add_f32_dpp v3, v5, v3 quad_perm:[2,3,0,1] row_mask:0xf bank_mask:0xf bound_ctrl:1
	v_cndmask_b32_e64 v5, v4, v0, s[44:45]
	v_cndmask_b32_e64 v0, v0, v4, s[44:45]
	v_cndmask_b32_e64 v4, v1, v3, s[46:47]
	v_cndmask_b32_e64 v1, v3, v1, s[46:47]
	ds_bpermute_b32 v3, v17, v4
	v_add_f32_dpp v0, v5, v0 quad_perm:[2,3,0,1] row_mask:0xf bank_mask:0xf bound_ctrl:1
	s_waitcnt lgkmcnt(0)
	v_add_f32_e32 v1, v1, v3
	v_cndmask_b32_e64 v3, v2, v0, s[46:47]
	v_cndmask_b32_e64 v0, v0, v2, s[46:47]
	ds_bpermute_b32 v2, v17, v3
	s_waitcnt lgkmcnt(0)
	v_add_f32_e32 v0, v0, v2
	v_cndmask_b32_e64 v2, v1, v0, s[48:49]
	v_cndmask_b32_e64 v0, v0, v1, s[48:49]
	ds_bpermute_b32 v1, v19, v2
	s_waitcnt lgkmcnt(0)
	v_add_f32_e32 v0, v0, v1
	ds_bpermute_b32 v1, v47, v0
	s_waitcnt lgkmcnt(0)
	v_add_f32_e32 v0, v0, v1
	ds_bpermute_b32 v1, v48, v0
	s_waitcnt lgkmcnt(0)
	v_add_f32_e32 v40, v0, v1
	s_nop 0
	v_readlane_b32 s8, v40, 0
	v_readlane_b32 s13, v40, 12
	v_readlane_b32 s24, v40, 2
	v_mul_f32_e32 v0, s8, v235
	v_exp_f32_e32 v0, v0
	v_readlane_b32 s23, v40, 10
	v_readlane_b32 s22, v40, 6
	v_readlane_b32 s20, v40, 14
	v_add_f32_e32 v0, 1.0, v0
	v_div_scale_f32 v1, s[8:9], v0, v0, 1.0
	v_rcp_f32_e32 v2, v1
	v_readlane_b32 s8, v254, 43
	v_readlane_b32 s10, v254, 45
	v_readlane_b32 s11, v254, 46
	v_fma_f32 v3, -v1, v2, 1.0
	v_fmac_f32_e32 v2, v3, v2
	v_div_scale_f32 v3, vcc, 1.0, v0, 1.0
	v_mul_f32_e32 v4, v3, v2
	v_fma_f32 v5, -v1, v4, v3
	v_fmac_f32_e32 v4, v5, v2
	v_fma_f32 v1, -v1, v4, v3
	v_div_fmas_f32 v1, v1, v2, v4
	v_div_fixup_f32 v41, v1, v0, 1.0
	global_load_dwordx4 v[0:3], v193, s[10:11] offset:48
	global_load_dwordx4 v[4:7], v193, s[10:11] offset:32
	global_load_dwordx4 v[8:11], v193, s[10:11] offset:16
	global_load_dwordx4 v[12:15], v193, s[10:11]
	v_readlane_b32 s8, v40, 8
	v_readlane_b32 s9, v254, 44
	v_readlane_b32 s19, v40, 1
	v_mul_f32_e32 v38, s8, v235
	v_exp_f32_e32 v38, v38
	v_readlane_b32 s18, v40, 9
	v_readlane_b32 s17, v40, 5
	v_readlane_b32 s16, v40, 13
	v_add_f32_e32 v38, 1.0, v38
	v_div_scale_f32 v39, s[8:9], v38, v38, 1.0
	v_rcp_f32_e32 v42, v39
	s_mov_b32 s9, 0xf149f2ca
	v_readlane_b32 s8, v40, 4
	v_readlane_b32 s15, v40, 3
	v_fma_f32 v43, -v39, v42, 1.0
	v_fmac_f32_e32 v42, v43, v42
	v_div_scale_f32 v43, vcc, 1.0, v38, 1.0
	v_mul_f32_e32 v44, v43, v42
	v_fma_f32 v45, -v39, v44, v43
	v_fmac_f32_e32 v44, v45, v42
	v_fma_f32 v39, -v39, v44, v43
	v_div_fmas_f32 v39, v39, v42, v44
	v_div_fixup_f32 v38, v39, v38, 1.0
	v_readlane_b32 s14, v40, 11
	v_readlane_b32 s12, v40, 7
	v_readlane_b32 s10, v40, 15
	s_waitcnt vmcnt(0)
	v_add_f32_e32 v12, v12, v41
	v_add_f32_e32 v39, v13, v38
	v_cmp_lt_f32_e32 vcc, s9, v12
	v_max_f32_e32 v40, 0xf149f2ca, v12
	s_nop 0
	v_cndmask_b32_e32 v12, 0, v41, vcc
	v_cmp_ngt_f32_e32 vcc, v39, v40
	s_cbranch_vccz .LBB0_586
	v_cmp_nlt_f32_e32 vcc, s9, v39
	s_mov_b32 s25, 0
	v_mov_b32_e32 v41, 0xf149f2ca
	v_mov_b32_e32 v13, 0
	s_cbranch_vccnz .LBB0_585
	s_mov_b32 s26, 1
	v_mov_b32_e32 v13, v38
	v_mov_b32_e32 v41, v39
